# attention online softmax: deferred running-max update (threshold 8 log2 units) skips most O rescales; M1 n-sum loop reads pipelined
# speedup vs baseline: 1.0297x; 1.0026x over previous
.LBB0_270:
	v_max_f32_e32 v48, v33, v33
	v_max_f32_e32 v49, v32, v32
	v_max_f32_e32 v48, v49, v48
	v_max3_f32 v48, v48, v34, v35
	v_max3_f32 v48, v48, v36, v37
	v_max3_f32 v48, v48, v38, v39
	v_max3_f32 v48, v48, v40, v41
	v_xor_b32_e32 v49, 32, v236
	v_add_u32_e32 v50, 64, v237
	v_max3_f32 v48, v48, v42, v43
	v_cmp_lt_i32_e32 vcc, v49, v50
	v_max3_f32 v48, v48, v44, v45
	v_max3_f32 v48, v48, v46, v47
	v_cndmask_b32_e32 v49, v236, v49, vcc
	v_lshlrev_b32_e32 v189, 2, v49
	ds_bpermute_b32 v49, v189, v48
	s_waitcnt lgkmcnt(0)
	v_max3_f32 v191, v233, v48, v49
	v_add_f32_e32 v48, 0x41000000, v233
	v_cmp_gt_f32_e32 vcc, v191, v48
	s_cbranch_vccnz .Latt_updA
	v_mov_b32_e32 v191, v233
	v_mov_b32_e32 v198, 1.0
	s_branch .LBB0_272
.Latt_updA:
	v_sub_f32_e32 v48, v233, v191
	v_exp_f32_e32 v198, v48
	s_nop 0
	v_pk_mul_f32 v[14:15], v[14:15], v[198:199] op_sel_hi:[1,0]
	v_pk_mul_f32 v[12:13], v[12:13], v[198:199] op_sel_hi:[1,0]
	v_pk_mul_f32 v[10:11], v[10:11], v[198:199] op_sel_hi:[1,0]
	v_pk_mul_f32 v[8:9], v[8:9], v[198:199] op_sel_hi:[1,0]
	v_pk_mul_f32 v[6:7], v[6:7], v[198:199] op_sel_hi:[1,0]
	v_pk_mul_f32 v[4:5], v[4:5], v[198:199] op_sel_hi:[1,0]
	v_pk_mul_f32 v[2:3], v[2:3], v[198:199] op_sel_hi:[1,0]
	v_pk_mul_f32 v[0:1], v[0:1], v[198:199] op_sel_hi:[1,0]
	v_pk_mul_f32 v[30:31], v[30:31], v[198:199] op_sel_hi:[1,0]
	v_pk_mul_f32 v[28:29], v[28:29], v[198:199] op_sel_hi:[1,0]
	v_pk_mul_f32 v[26:27], v[26:27], v[198:199] op_sel_hi:[1,0]
	v_pk_mul_f32 v[24:25], v[24:25], v[198:199] op_sel_hi:[1,0]
	v_pk_mul_f32 v[22:23], v[22:23], v[198:199] op_sel_hi:[1,0]
	v_pk_mul_f32 v[20:21], v[20:21], v[198:199] op_sel_hi:[1,0]
	v_pk_mul_f32 v[18:19], v[18:19], v[198:199] op_sel_hi:[1,0]
	v_pk_mul_f32 v[16:17], v[16:17], v[198:199] op_sel_hi:[1,0]

.LBB0_278:
	v_max_f32_e32 v48, v33, v33
	v_max_f32_e32 v49, v32, v32
	v_max_f32_e32 v48, v49, v48
	v_max3_f32 v48, v48, v34, v35
	v_max3_f32 v48, v48, v36, v37
	v_max3_f32 v48, v48, v38, v39
	v_max3_f32 v48, v48, v40, v41
	v_max3_f32 v48, v48, v42, v43
	v_max3_f32 v48, v48, v44, v45
	v_max3_f32 v48, v48, v46, v47
	ds_bpermute_b32 v49, v189, v48
	s_waitcnt lgkmcnt(0)
	v_max3_f32 v233, v191, v48, v49
	v_add_f32_e32 v48, 0x41000000, v191
	v_cmp_gt_f32_e32 vcc, v233, v48
	s_cbranch_vccnz .Latt_updB
	v_mov_b32_e32 v233, v191
	v_mov_b32_e32 v48, 1.0
	s_branch .LBB0_280
.Latt_updB:
	v_sub_f32_e32 v48, v191, v233
	v_exp_f32_e32 v48, v48
	s_nop 0
	v_pk_mul_f32 v[30:31], v[30:31], v[48:49] op_sel_hi:[1,0]
	v_pk_mul_f32 v[28:29], v[28:29], v[48:49] op_sel_hi:[1,0]
	v_pk_mul_f32 v[26:27], v[26:27], v[48:49] op_sel_hi:[1,0]
	v_pk_mul_f32 v[24:25], v[24:25], v[48:49] op_sel_hi:[1,0]
	v_pk_mul_f32 v[22:23], v[22:23], v[48:49] op_sel_hi:[1,0]
	v_pk_mul_f32 v[20:21], v[20:21], v[48:49] op_sel_hi:[1,0]
	v_pk_mul_f32 v[18:19], v[18:19], v[48:49] op_sel_hi:[1,0]
	v_pk_mul_f32 v[16:17], v[16:17], v[48:49] op_sel_hi:[1,0]
	v_pk_mul_f32 v[14:15], v[14:15], v[48:49] op_sel_hi:[1,0]
	v_pk_mul_f32 v[12:13], v[12:13], v[48:49] op_sel_hi:[1,0]
	v_pk_mul_f32 v[10:11], v[10:11], v[48:49] op_sel_hi:[1,0]
	v_pk_mul_f32 v[8:9], v[8:9], v[48:49] op_sel_hi:[1,0]
	v_pk_mul_f32 v[6:7], v[6:7], v[48:49] op_sel_hi:[1,0]
	v_pk_mul_f32 v[4:5], v[4:5], v[48:49] op_sel_hi:[1,0]
	v_pk_mul_f32 v[2:3], v[2:3], v[48:49] op_sel_hi:[1,0]
	v_pk_mul_f32 v[0:1], v[0:1], v[48:49] op_sel_hi:[1,0]

.LBB0_377:
	s_or_b64 exec, exec, s[0:1]
	v_add3_u32 v5, v64, v112, v65
	ds_write_b128 v5, v[0:3] offset:17280
	v_lshrrev_b32_e32 v0, 2, v67
	v_and_b32_e32 v98, 8, v0
	v_lshlrev_b32_e32 v0, 5, v68
	v_and_b32_e32 v0, 32, v0
	v_add_u32_e32 v2, v105, v0
	v_lshlrev_b32_e32 v0, 3, v104
	s_waitcnt lgkmcnt(1)
	v_lshrrev_b32_e32 v4, 2, v69
	v_and_b32_e32 v3, 24, v0
	v_lshlrev_b64 v[0:1], 15, v[96:97]
	v_lshl_add_u64 v[100:101], s[2:3], 0, v[0:1]
	v_or_b32_e32 v0, v98, v4
	v_mul_u32_u24_e32 v0, 0x120, v0
	v_add3_u32 v106, v2, v3, v0
	v_lshl_add_u32 v102, v99, 7, v106
	s_waitcnt lgkmcnt(0)
	s_barrier
	ds_read_b64_tr_b16 v[0:1], v106
	ds_read_b64_tr_b16 v[2:3], v106 offset:1152
	ds_read_b64_tr_b16 v[4:5], v106 offset:64
	ds_read_b64_tr_b16 v[6:7], v106 offset:1216
	ds_read_b64_tr_b16 v[88:89], v102 offset:18432
	ds_read_b64_tr_b16 v[90:91], v102 offset:19584
	ds_read_b64_tr_b16 v[92:93], v102 offset:18496
	ds_read_b64_tr_b16 v[94:95], v102 offset:19648
	s_waitcnt lgkmcnt(2)
	v_mfma_f32_32x32x16_bf16 v[48:63], v[0:3], v[88:91], 0
	ds_read_b64_tr_b16 v[64:65], v106 offset:4608
	ds_read_b64_tr_b16 v[66:67], v106 offset:5760
	ds_read_b64_tr_b16 v[68:69], v106 offset:4672
	ds_read_b64_tr_b16 v[70:71], v106 offset:5824
	ds_read_b64_tr_b16 v[80:81], v102 offset:23040
	ds_read_b64_tr_b16 v[82:83], v102 offset:24192
	ds_read_b64_tr_b16 v[84:85], v102 offset:23104
	ds_read_b64_tr_b16 v[86:87], v102 offset:24256
	s_mov_b64 s[4:5], 0xd202000
	s_mov_b32 s0, 0
	s_waitcnt lgkmcnt(8)
	v_mfma_f32_32x32x16_bf16 v[32:47], v[0:3], v[92:95], 0
	v_mfma_f32_32x32x16_bf16 v[16:31], v[4:7], v[88:91], 0
	v_mfma_f32_32x32x16_bf16 v[0:15], v[4:7], v[92:95], 0
	s_waitcnt lgkmcnt(2)
	v_mfma_f32_32x32x16_bf16 v[48:63], v[64:67], v[80:83], v[48:63]
	s_waitcnt lgkmcnt(0)
	v_mfma_f32_32x32x16_bf16 v[32:47], v[64:67], v[84:87], v[32:47]
	v_mfma_f32_32x32x16_bf16 v[16:31], v[68:71], v[80:83], v[16:31]
	v_mfma_f32_32x32x16_bf16 v[0:15], v[68:71], v[84:87], v[0:15]
	ds_read_b64_tr_b16 v[64:65], v106 offset:9216
	ds_read_b64_tr_b16 v[66:67], v106 offset:10368
	ds_read_b64_tr_b16 v[68:69], v106 offset:9280
	ds_read_b64_tr_b16 v[70:71], v106 offset:10432
	ds_read_b64_tr_b16 v[72:73], v102 offset:27648
	ds_read_b64_tr_b16 v[74:75], v102 offset:28800
	ds_read_b64_tr_b16 v[76:77], v102 offset:27712
	ds_read_b64_tr_b16 v[78:79], v102 offset:28864
	s_waitcnt lgkmcnt(2)
	v_mfma_f32_32x32x16_bf16 v[48:63], v[64:67], v[72:75], v[48:63]
	s_waitcnt lgkmcnt(0)
	v_mfma_f32_32x32x16_bf16 v[32:47], v[64:67], v[76:79], v[32:47]
	v_mfma_f32_32x32x16_bf16 v[16:31], v[68:71], v[72:75], v[16:31]
	v_mfma_f32_32x32x16_bf16 v[0:15], v[68:71], v[76:79], v[0:15]
	ds_read_b64_tr_b16 v[108:109], v106 offset:13824
	ds_read_b64_tr_b16 v[110:111], v106 offset:14976
	ds_read_b64_tr_b16 v[114:115], v106 offset:13888
	ds_read_b64_tr_b16 v[116:117], v106 offset:15040
	ds_read_b64_tr_b16 v[64:65], v102 offset:32256
	ds_read_b64_tr_b16 v[66:67], v102 offset:33408
	ds_read_b64_tr_b16 v[68:69], v102 offset:32320
	ds_read_b64_tr_b16 v[70:71], v102 offset:33472
	v_lshlrev_b32_e32 v102, 8, v104
	v_and_b32_e32 v102, 0x1f00, v102
	v_lshl_or_b32 v112, v99, 14, v102
	v_lshl_add_u64 v[100:101], v[100:101], 0, v[112:113]
	v_mov_b32_e32 v99, v113
	v_or_b32_e32 v112, 16, v98
	s_waitcnt lgkmcnt(2)
	v_mfma_f32_32x32x16_bf16 v[48:63], v[108:111], v[64:67], v[48:63]
	s_waitcnt lgkmcnt(0)
	v_mfma_f32_32x32x16_bf16 v[32:47], v[108:111], v[68:71], v[32:47]
	v_mfma_f32_32x32x16_bf16 v[16:31], v[114:117], v[64:67], v[16:31]
	v_mfma_f32_32x32x16_bf16 v[0:15], v[114:117], v[68:71], v[0:15]
	v_lshlrev_b32_e32 v112, 1, v98
	v_lshl_add_u64 v[102:103], v[100:101], 0, v[112:113]
	v_lshl_add_u64 v[108:109], v[102:103], 0, s[4:5]
	v_lshl_add_u64 v[102:103], v[102:103], 0, s[56:57]
	s_nop 9
	v_cvt_pk_bf16_f32 v48, v48, v49
	v_cvt_pk_bf16_f32 v49, v50, v51
	v_cvt_pk_bf16_f32 v50, v52, v53
	v_cvt_pk_bf16_f32 v51, v54, v55
	v_cvt_pk_bf16_f32 v52, v56, v57
	v_cvt_pk_bf16_f32 v53, v58, v59
	v_cvt_pk_bf16_f32 v54, v60, v61
	v_cvt_pk_bf16_f32 v55, v62, v63
	v_permlane32_swap_b32_e32 v48, v50
	v_permlane32_swap_b32_e32 v49, v51
	v_permlane32_swap_b32_e32 v52, v54
	v_permlane32_swap_b32_e32 v53, v55
	global_store_dwordx4 v[102:103], v[48:51], off
	global_store_dwordx4 v[102:103], v[52:55], off offset:32
	v_cvt_pk_bf16_f32 v32, v32, v33
	v_cvt_pk_bf16_f32 v33, v34, v35
	v_cvt_pk_bf16_f32 v34, v36, v37
	v_cvt_pk_bf16_f32 v35, v38, v39
	v_cvt_pk_bf16_f32 v36, v40, v41
	v_cvt_pk_bf16_f32 v37, v42, v43
	v_cvt_pk_bf16_f32 v38, v44, v45
	v_cvt_pk_bf16_f32 v39, v46, v47
	v_permlane32_swap_b32_e32 v32, v34
	v_permlane32_swap_b32_e32 v33, v35
	v_permlane32_swap_b32_e32 v36, v38
	v_permlane32_swap_b32_e32 v37, v39
	global_store_dwordx4 v[108:109], v[32:35], off
	global_store_dwordx4 v[108:109], v[36:39], off offset:32
	v_cvt_pk_bf16_f32 v16, v16, v17
	v_cvt_pk_bf16_f32 v17, v18, v19
	v_cvt_pk_bf16_f32 v18, v20, v21
	v_cvt_pk_bf16_f32 v19, v22, v23
	v_cvt_pk_bf16_f32 v20, v24, v25
	v_cvt_pk_bf16_f32 v21, v26, v27
	v_cvt_pk_bf16_f32 v22, v28, v29
	v_cvt_pk_bf16_f32 v23, v30, v31
	v_permlane32_swap_b32_e32 v16, v18
	v_permlane32_swap_b32_e32 v17, v19
	v_permlane32_swap_b32_e32 v20, v22
	v_permlane32_swap_b32_e32 v21, v23
	global_store_dwordx4 v[102:103], v[16:19], off offset:64
	global_store_dwordx4 v[102:103], v[20:23], off offset:96
	v_cvt_pk_bf16_f32 v0, v0, v1
	v_cvt_pk_bf16_f32 v1, v2, v3
	v_cvt_pk_bf16_f32 v2, v4, v5
	v_cvt_pk_bf16_f32 v3, v6, v7
	v_cvt_pk_bf16_f32 v4, v8, v9
	v_cvt_pk_bf16_f32 v5, v10, v11
	v_cvt_pk_bf16_f32 v6, v12, v13
	v_cvt_pk_bf16_f32 v7, v14, v15
	v_permlane32_swap_b32_e32 v0, v2
	v_permlane32_swap_b32_e32 v1, v3
	v_permlane32_swap_b32_e32 v4, v6
	v_permlane32_swap_b32_e32 v5, v7
	global_store_dwordx4 v[108:109], v[0:3], off offset:64
	global_store_dwordx4 v[108:109], v[4:7], off offset:96
	ds_read_b64_tr_b16 v[0:1], v106 offset:128
	ds_read_b64_tr_b16 v[2:3], v106 offset:1280
	ds_read_b64_tr_b16 v[4:5], v106 offset:192
	ds_read_b64_tr_b16 v[6:7], v106 offset:1344
	s_waitcnt lgkmcnt(2)
	v_mfma_f32_32x32x16_bf16 v[32:47], v[0:3], v[92:95], 0
	v_mfma_f32_32x32x16_bf16 v[48:63], v[0:3], v[88:91], 0
	s_waitcnt lgkmcnt(0)
	v_mfma_f32_32x32x16_bf16 v[16:31], v[4:7], v[88:91], 0
	v_mfma_f32_32x32x16_bf16 v[0:15], v[4:7], v[92:95], 0
	ds_read_b64_tr_b16 v[88:89], v106 offset:4736
	ds_read_b64_tr_b16 v[90:91], v106 offset:5888
	ds_read_b64_tr_b16 v[92:93], v106 offset:4800
	ds_read_b64_tr_b16 v[94:95], v106 offset:5952
	s_waitcnt lgkmcnt(2)
	v_mfma_f32_32x32x16_bf16 v[32:47], v[88:91], v[84:87], v[32:47]
	s_waitcnt lgkmcnt(0)
	v_mfma_f32_32x32x16_bf16 v[0:15], v[92:95], v[84:87], v[0:15]
	v_mfma_f32_32x32x16_bf16 v[48:63], v[88:91], v[80:83], v[48:63]
	v_mfma_f32_32x32x16_bf16 v[16:31], v[92:95], v[80:83], v[16:31]
	ds_read_b64_tr_b16 v[80:81], v106 offset:9344
	ds_read_b64_tr_b16 v[82:83], v106 offset:10496
	ds_read_b64_tr_b16 v[84:85], v106 offset:9408
	ds_read_b64_tr_b16 v[86:87], v106 offset:10560
	s_waitcnt lgkmcnt(2)
	v_mfma_f32_32x32x16_bf16 v[32:47], v[80:83], v[76:79], v[32:47]
	s_waitcnt lgkmcnt(0)
	v_mfma_f32_32x32x16_bf16 v[0:15], v[84:87], v[76:79], v[0:15]
	v_mfma_f32_32x32x16_bf16 v[48:63], v[80:83], v[72:75], v[48:63]
	v_mfma_f32_32x32x16_bf16 v[16:31], v[84:87], v[72:75], v[16:31]
	ds_read_b64_tr_b16 v[72:73], v106 offset:13952
	ds_read_b64_tr_b16 v[74:75], v106 offset:15104
	ds_read_b64_tr_b16 v[76:77], v106 offset:14016
	ds_read_b64_tr_b16 v[78:79], v106 offset:15168
	s_waitcnt lgkmcnt(2)
	v_mfma_f32_32x32x16_bf16 v[32:47], v[72:75], v[68:71], v[32:47]
	s_waitcnt lgkmcnt(0)
	v_mfma_f32_32x32x16_bf16 v[0:15], v[76:79], v[68:71], v[0:15]
	v_mfma_f32_32x32x16_bf16 v[48:63], v[72:75], v[64:67], v[48:63]
	v_mfma_f32_32x32x16_bf16 v[16:31], v[76:79], v[64:67], v[16:31]
	s_nop 15
	v_cvt_pk_bf16_f32 v48, v48, v49
	v_cvt_pk_bf16_f32 v49, v50, v51
	v_cvt_pk_bf16_f32 v50, v52, v53
	v_cvt_pk_bf16_f32 v51, v54, v55
	v_cvt_pk_bf16_f32 v52, v56, v57
	v_cvt_pk_bf16_f32 v53, v58, v59
	v_cvt_pk_bf16_f32 v54, v60, v61
	v_cvt_pk_bf16_f32 v55, v62, v63
	v_permlane32_swap_b32_e32 v48, v50
	v_permlane32_swap_b32_e32 v49, v51
	v_permlane32_swap_b32_e32 v52, v54
	v_permlane32_swap_b32_e32 v53, v55
	global_store_dwordx4 v[102:103], v[48:51], off offset:128
	global_store_dwordx4 v[102:103], v[52:55], off offset:160
	v_cvt_pk_bf16_f32 v32, v32, v33
	v_cvt_pk_bf16_f32 v33, v34, v35
	v_cvt_pk_bf16_f32 v34, v36, v37
	v_cvt_pk_bf16_f32 v35, v38, v39
	v_cvt_pk_bf16_f32 v36, v40, v41
	v_cvt_pk_bf16_f32 v37, v42, v43
	v_cvt_pk_bf16_f32 v38, v44, v45
	v_cvt_pk_bf16_f32 v39, v46, v47
	v_permlane32_swap_b32_e32 v32, v34
	v_permlane32_swap_b32_e32 v33, v35
	v_permlane32_swap_b32_e32 v36, v38
	v_permlane32_swap_b32_e32 v37, v39
	global_store_dwordx4 v[108:109], v[32:35], off offset:128
	global_store_dwordx4 v[108:109], v[36:39], off offset:160
	v_cvt_pk_bf16_f32 v16, v16, v17
	v_cvt_pk_bf16_f32 v17, v18, v19
	v_cvt_pk_bf16_f32 v18, v20, v21
	v_cvt_pk_bf16_f32 v19, v22, v23
	v_cvt_pk_bf16_f32 v20, v24, v25
	v_cvt_pk_bf16_f32 v21, v26, v27
	v_cvt_pk_bf16_f32 v22, v28, v29
	v_cvt_pk_bf16_f32 v23, v30, v31
	v_permlane32_swap_b32_e32 v16, v18
	v_permlane32_swap_b32_e32 v17, v19
	v_permlane32_swap_b32_e32 v20, v22
	v_permlane32_swap_b32_e32 v21, v23
	global_store_dwordx4 v[102:103], v[16:19], off offset:192
	global_store_dwordx4 v[102:103], v[20:23], off offset:224
	v_cvt_pk_bf16_f32 v0, v0, v1
	v_cvt_pk_bf16_f32 v1, v2, v3
	v_cvt_pk_bf16_f32 v2, v4, v5
	v_cvt_pk_bf16_f32 v3, v6, v7
	v_cvt_pk_bf16_f32 v4, v8, v9
	v_cvt_pk_bf16_f32 v5, v10, v11
	v_cvt_pk_bf16_f32 v6, v12, v13
	v_cvt_pk_bf16_f32 v7, v14, v15
	v_permlane32_swap_b32_e32 v0, v2
	v_permlane32_swap_b32_e32 v1, v3
	v_permlane32_swap_b32_e32 v4, v6
	v_permlane32_swap_b32_e32 v5, v7
	global_store_dwordx4 v[108:109], v[0:3], off offset:192
	global_store_dwordx4 v[108:109], v[4:7], off offset:224
	s_nop 1
	v_and_b32_e32 v0, 0x7f, v104
	v_lshl_add_u32 v1, v0, 1, v105
	v_mov_b32_e32 v2, 0
.LBB0_378:
	v_add_u32_e32 v3, s0, v1
	ds_read_u16 v4, v3
	ds_read_u16 v5, v3 offset:288
	ds_read_u16 v6, v3 offset:576
	ds_read_u16 v7, v3 offset:864
	ds_read_u16 v8, v3 offset:1152
	ds_read_u16 v9, v3 offset:1440
	ds_read_u16 v10, v3 offset:1728
	ds_read_u16 v11, v3 offset:2016
	s_addk_i32 s0, 0x900
	s_cmpk_lg_i32 s0, 0x4800
	s_waitcnt lgkmcnt(7)
	v_lshlrev_b32_e32 v4, 16, v4
	v_add_f32_e32 v2, v2, v4
	s_waitcnt lgkmcnt(6)
	v_lshlrev_b32_e32 v5, 16, v5
	v_add_f32_e32 v2, v2, v5
	s_waitcnt lgkmcnt(5)
	v_lshlrev_b32_e32 v6, 16, v6
	v_add_f32_e32 v2, v2, v6
	s_waitcnt lgkmcnt(4)
	v_lshlrev_b32_e32 v7, 16, v7
	v_add_f32_e32 v2, v2, v7
	s_waitcnt lgkmcnt(3)
	v_lshlrev_b32_e32 v8, 16, v8
	v_add_f32_e32 v2, v2, v8
	s_waitcnt lgkmcnt(2)
	v_lshlrev_b32_e32 v9, 16, v9
	v_add_f32_e32 v2, v2, v9
	s_waitcnt lgkmcnt(1)
	v_lshlrev_b32_e32 v10, 16, v10
	v_add_f32_e32 v2, v2, v10
	s_waitcnt lgkmcnt(0)
	v_lshlrev_b32_e32 v11, 16, v11
	v_add_f32_e32 v2, v2, v11
	s_cbranch_scc1 .LBB0_378
	v_lshlrev_b64 v[4:5], 9, v[96:97]
	v_lshl_add_u64 v[4:5], s[2:3], 0, v[4:5]
	v_lshlrev_b32_e32 v112, 2, v0
	v_lshl_add_u64 v[0:1], v[4:5], 0, v[112:113]
	v_add_co_u32_e32 v0, vcc, 0x200000, v0
	s_add_i32 s12, s12, s13
	s_nop 0
	v_addc_co_u32_e32 v1, vcc, 0, v1, vcc
	global_store_dword v[0:1], v2, off
	s_barrier
	s_cmp_ge_i32 s12, s14
	s_cbranch_scc0 .LBB0_311
